# attention loop: static s_setprio 1 for waves 0-3 (older half) over the tile loop
# speedup vs baseline: 1.0053x; 1.0005x over previous
; #define LAS __attribute__((address_space(3)))
; __device__ __forceinline__ void attn_block(LAS unsigned char* lds, const bf16_t* P, bf16_t* mix, int b, int h, int qb, float lam, float outscale, const float* subln) {
;     ...
;     for (int kt = 0; kt < ntiles; ++kt) {
;         __syncthreads();
;         const int buf = kt & 1;
;         if (kt + 1 < ntiles) {
;             const size_t ro = (size_t)(64 * (kt + 1)) * INC;
;             kr0 = *(const u32x4*)(kg + ro + (size_t)srow * INC); kr1 = *(const u32x4*)(kg + ro + (size_t)(srow + 32) * INC);
;             vr0 = *(const u32x4*)(vg + ro + (size_t)srow * INC); vr1 = *(const u32x4*)(vg + ro + (size_t)(srow + 32) * INC);
;         }
;         const int kb = 64 * kt;
;         if (kb <= qw0 + 31) {
;             LAS const unsigned char* Kb = lds + ATT_K0 + buf * 16384;
;             LAS const unsigned char* Vb = lds + ATT_V0 + buf * 16384;
;             f32x16 s0, s1;
; #pragma unroll
;             for (int j = 0; j < 16; ++j) { s0[j] = 0.f; s1[j] = 0.f; }
;             bf16x8 ka[4][2];
; #pragma unroll
;             for (int ks = 0; ks < 4; ++ks) { ka[ks][0] = *(const LAS bf16x8*)(Kb + kbase[ks]); ka[ks][1] = *(const LAS bf16x8*)(Kb + kbase[ks] + 8192); }
.Lat1_pre_done:
	s_waitcnt lgkmcnt(0)
	s_barrier
	s_cmpk_lt_u32 s42, 0x100
	s_cbranch_scc0 .Lat1_noprio
	s_setprio 1
.Lat1_noprio:
	ds_read_b128 v[136:139], v180
	ds_read_b128 v[140:143], v180 offset:8192
	ds_read_b128 v[204:207], v181
	ds_read_b128 v[208:211], v181 offset:8192
	ds_read_b128 v[238:241], v178
	ds_read_b128 v[242:245], v178 offset:8192
	ds_read_b128 v[246:249], v177
	ds_read_b128 v[250:253], v177 offset:8192
	s_add_i32 s73, s71, 384
	s_cmp_le_u32 s73, s36
	s_cbranch_scc0 .Lat1_U_none
	v_add_u32_e32 v114, 0x10000, v173
	v_add_u32_e32 v115, 0x10000, v174
	v_add_u32_e32 v116, 0x10000, v170
	v_add_u32_e32 v117, 0x10000, v172
	v_add_u32_e32 v118, 0x10000, v168
	v_add_u32_e32 v119, 0x10000, v171
	v_add_u32_e32 v120, 0x10000, v145
	v_add_u32_e32 v121, 0x10000, v169
	v_add_u32_e32 v126, 0x10000, v180
	v_add_u32_e32 v127, 0x10000, v181
	v_add_u32_e32 v128, 0x10000, v178
	v_add_u32_e32 v129, 0x10000, v177
	s_lshl_b32 s70, s42, 4
	s_and_b32 s70, s70, 0x1c00
	s_mov_b32 s73, s70

; #define LAS __attribute__((address_space(3)))
; __device__ __forceinline__ void attn_block(LAS unsigned char* lds, const bf16_t* P, bf16_t* mix, int b, int h, int qb, float lam, float outscale, const float* subln) {
;     ...
;     }
;     const float ltot = lrun + __shfl_xor(lrun, 32);
;     const float inv = 1.0f / ltot;
;     LAS float* X = (LAS float*)(lds + ATT_X) + (wq * 32 + r32) * ATT_XS;
.Lat1_exit:
	s_setprio 0
	s_waitcnt vmcnt(0) lgkmcnt(0)
	s_barrier
	s_nop 7
	s_nop 4
	s_branch .LBB0_112

; #define LAS __attribute__((address_space(3)))
; __device__ __forceinline__ void attn_block(LAS unsigned char* lds, const bf16_t* P, bf16_t* mix, int b, int h, int qb, float lam, float outscale, const float* subln) {
;     ...
;     for (int kt = 0; kt < ntiles; ++kt) {
;         __syncthreads();
;         const int buf = kt & 1;
;         if (kt + 1 < ntiles) {
;             const size_t ro = (size_t)(64 * (kt + 1)) * INC;
;             kr0 = *(const u32x4*)(kg + ro + (size_t)srow * INC); kr1 = *(const u32x4*)(kg + ro + (size_t)(srow + 32) * INC);
;             vr0 = *(const u32x4*)(vg + ro + (size_t)srow * INC); vr1 = *(const u32x4*)(vg + ro + (size_t)(srow + 32) * INC);
;         }
;         const int kb = 64 * kt;
;         if (kb <= qw0 + 31) {
;             LAS const unsigned char* Kb = lds + ATT_K0 + buf * 16384;
;             LAS const unsigned char* Vb = lds + ATT_V0 + buf * 16384;
;             f32x16 s0, s1;
; #pragma unroll
;             for (int j = 0; j < 16; ++j) { s0[j] = 0.f; s1[j] = 0.f; }
;             bf16x8 ka[4][2];
; #pragma unroll
;             for (int ks = 0; ks < 4; ++ks) { ka[ks][0] = *(const LAS bf16x8*)(Kb + kbase[ks]); ka[ks][1] = *(const LAS bf16x8*)(Kb + kbase[ks] + 8192); }
.Lat2_pre_done:
	s_waitcnt lgkmcnt(0)
	s_barrier
	s_cmpk_lt_u32 s33, 0x100
	s_cbranch_scc0 .Lat2_noprio
	s_setprio 1
.Lat2_noprio:
	ds_read_b128 v[136:139], v178
	ds_read_b128 v[140:143], v178 offset:8192
	ds_read_b128 v[204:207], v181
	ds_read_b128 v[208:211], v181 offset:8192
	ds_read_b128 v[238:241], v180
	ds_read_b128 v[242:245], v180 offset:8192
	ds_read_b128 v[246:249], v179
	ds_read_b128 v[250:253], v179 offset:8192
	s_add_i32 s62, s50, 384
	s_cmp_le_u32 s62, s2
	s_cbranch_scc0 .Lat2_U_none
	v_add_u32_e32 v114, 0x10000, v168
	v_add_u32_e32 v115, 0x10000, v175
	v_add_u32_e32 v116, 0x10000, v172
	v_add_u32_e32 v117, 0x10000, v174
	v_add_u32_e32 v118, 0x10000, v170
	v_add_u32_e32 v119, 0x10000, v173
	v_add_u32_e32 v120, 0x10000, v169
	v_add_u32_e32 v121, 0x10000, v171
	v_add_u32_e32 v126, 0x10000, v178
	v_add_u32_e32 v127, 0x10000, v181
	v_add_u32_e32 v128, 0x10000, v180
	v_add_u32_e32 v129, 0x10000, v179
	s_lshl_b32 s39, s33, 4
	s_and_b32 s39, s39, 0x1c00
	s_mov_b32 s62, s39
